# grid barrier: XCD leaders wait on the top-level arrival count itself (no separate top generation word / atomic)
# speedup vs baseline: 1.0058x; 1.0029x over previous
.LBB0_80:
	s_or_b64 exec, exec, s[4:5]
	v_cvt_f32_u32_e32 v3, v0
	s_waitcnt vmcnt(0)
	v_readfirstlane_b32 s0, v2
	s_add_u32 s4, s26, 0xc3500
	s_addc_u32 s5, s27, 0
	v_rcp_iflag_f32_e32 v3, v3
	v_add_u32_e32 v1, s0, v1
	v_add_u32_e32 v4, 1, v1
	s_mov_b64 s[10:11], -1
	v_mul_f32_e32 v2, 0x4f7ffffe, v3
	v_cvt_u32_f32_e32 v2, v2
	v_sub_u32_e32 v3, 0, v0
	v_mul_lo_u32 v3, v3, v2
	v_mul_hi_u32 v3, v2, v3
	v_add_u32_e32 v2, v2, v3
	v_mul_hi_u32 v2, v1, v2
	v_mul_lo_u32 v3, v2, v0
	v_sub_u32_e32 v1, v1, v3
	v_add_u32_e32 v5, 1, v2
	v_cmp_ge_u32_e32 vcc, v1, v0
	v_sub_u32_e32 v3, v1, v0
	s_nop 0
	v_cndmask_b32_e32 v2, v2, v5, vcc
	v_cndmask_b32_e32 v1, v1, v3, vcc
	v_add_u32_e32 v3, 1, v2
	v_cmp_ge_u32_e32 vcc, v1, v0
	s_nop 1
	v_cndmask_b32_e32 v2, v2, v3, vcc
	v_mul_lo_u32 v1, v0, v2
	v_add_u32_e32 v0, v1, v0
	v_cmp_ne_u32_e32 vcc, v4, v0
	s_and_saveexec_b64 s[0:1], vcc
	s_cbranch_execz .Lxb_l0
	v_mov_b32_e32 v1, 0xc3000
	s_mov_b32 s12, 0
.Lxb_v0:
	global_load_dword v2, v1, s[26:27] offset:1024 sc1
	s_add_u32 s12, s12, 1
	s_waitcnt vmcnt(0)
	v_cmp_lt_u32_e32 vcc, v2, v0
	s_cbranch_vccz .Lxb_l0
	s_cmp_lt_u32 s12, 0x4000
	s_cbranch_scc0 .Lxb_l0
	s_sleep 1
	s_branch .Lxb_v0
.Lxb_l0:
	s_or_b64 exec, exec, s[0:1]
.LBB0_94:
	s_or_b64 exec, exec, s[0:1]
	s_mov_b64 s[0:1], exec
	v_mbcnt_lo_u32_b32 v0, s0, 0
	v_mbcnt_hi_u32_b32 v0, s1, v0
	v_cmp_eq_u32_e32 vcc, 0, v0
	s_waitcnt vmcnt(0)
	buffer_inv sc1
	s_and_saveexec_b64 s[4:5], vcc
	s_cbranch_execz .LBB0_96
	s_bcnt1_i32_b64 s0, s[0:1]
	v_mov_b32_e32 v0, 0x2000
	v_mov_b32_e32 v1, s0
	global_atomic_add v0, v1, s[8:9] offset:1024

.LBB0_278:
	s_or_b64 exec, exec, s[4:5]
	v_cvt_f32_u32_e32 v3, v0
	s_waitcnt vmcnt(0)
	v_readfirstlane_b32 s0, v2
	s_add_u32 s4, s26, 0xc3500
	s_addc_u32 s5, s27, 0
	v_rcp_iflag_f32_e32 v3, v3
	v_add_u32_e32 v1, s0, v1
	v_add_u32_e32 v4, 1, v1
	s_mov_b64 s[12:13], -1
	v_mul_f32_e32 v2, 0x4f7ffffe, v3
	v_cvt_u32_f32_e32 v2, v2
	v_sub_u32_e32 v3, 0, v0
	v_mul_lo_u32 v3, v3, v2
	v_mul_hi_u32 v3, v2, v3
	v_add_u32_e32 v2, v2, v3
	v_mul_hi_u32 v2, v1, v2
	v_mul_lo_u32 v3, v2, v0
	v_sub_u32_e32 v1, v1, v3
	v_add_u32_e32 v5, 1, v2
	v_cmp_ge_u32_e32 vcc, v1, v0
	v_sub_u32_e32 v3, v1, v0
	s_nop 0
	v_cndmask_b32_e32 v2, v2, v5, vcc
	v_cndmask_b32_e32 v1, v1, v3, vcc
	v_add_u32_e32 v3, 1, v2
	v_cmp_ge_u32_e32 vcc, v1, v0
	s_nop 1
	v_cndmask_b32_e32 v2, v2, v3, vcc
	v_mul_lo_u32 v1, v0, v2
	v_add_u32_e32 v0, v1, v0
	v_cmp_ne_u32_e32 vcc, v4, v0
	s_and_saveexec_b64 s[0:1], vcc
	s_cbranch_execz .Lxb_l1
	v_mov_b32_e32 v1, 0xc3000
	s_mov_b32 s12, 0

.Lxb_l1:
	s_or_b64 exec, exec, s[0:1]
.LBB0_292:
	s_or_b64 exec, exec, s[0:1]
	s_mov_b64 s[0:1], exec
	v_mbcnt_lo_u32_b32 v0, s0, 0
	v_mbcnt_hi_u32_b32 v0, s1, v0
	v_cmp_eq_u32_e32 vcc, 0, v0
	s_waitcnt vmcnt(0)
	buffer_inv sc1
	s_and_saveexec_b64 s[4:5], vcc
	s_cbranch_execz .LBB0_294
	s_bcnt1_i32_b64 s0, s[0:1]
	v_mov_b32_e32 v0, 0x2000
	v_mov_b32_e32 v1, s0
	global_atomic_add v0, v1, s[8:9] offset:1024

.Lxb_l2:
	s_or_b64 exec, exec, s[0:1]
.LBB0_523:
	s_or_b64 exec, exec, s[0:1]
	s_mov_b64 s[0:1], exec
	v_mbcnt_lo_u32_b32 v0, s0, 0
	v_mbcnt_hi_u32_b32 v0, s1, v0
	v_cmp_eq_u32_e32 vcc, 0, v0
	s_waitcnt vmcnt(0)
	buffer_inv sc1
	s_and_saveexec_b64 s[4:5], vcc
	s_cbranch_execz .LBB0_525
	s_bcnt1_i32_b64 s0, s[0:1]
	v_mov_b32_e32 v0, 0x2000
	v_mov_b32_e32 v1, s0
	global_atomic_add v0, v1, s[8:9] offset:1024

.Lxb_l3:
	s_or_b64 exec, exec, s[0:1]
.LBB0_596:
	s_or_b64 exec, exec, s[0:1]
	s_mov_b64 s[0:1], exec
	v_mbcnt_lo_u32_b32 v0, s0, 0
	v_mbcnt_hi_u32_b32 v0, s1, v0
	v_cmp_eq_u32_e32 vcc, 0, v0
	s_waitcnt vmcnt(0)
	buffer_inv sc1
	s_and_saveexec_b64 s[4:5], vcc
	s_cbranch_execz .LBB0_598
	s_bcnt1_i32_b64 s0, s[0:1]
	v_mov_b32_e32 v0, 0x2000
	v_mov_b32_e32 v1, s0
	global_atomic_add v0, v1, s[8:9] offset:1024

.Lxb_l4:
	s_or_b64 exec, exec, s[0:1]
.LBB0_781:
	s_or_b64 exec, exec, s[0:1]
	s_mov_b64 s[0:1], exec
	v_mbcnt_lo_u32_b32 v0, s0, 0
	v_mbcnt_hi_u32_b32 v0, s1, v0
	v_cmp_eq_u32_e32 vcc, 0, v0
	s_waitcnt vmcnt(0)
	buffer_inv sc1
	s_and_saveexec_b64 s[4:5], vcc
	s_cbranch_execz .LBB0_783
	s_bcnt1_i32_b64 s0, s[0:1]
	v_mov_b32_e32 v0, 0x2000
	v_mov_b32_e32 v1, s0
	global_atomic_add v0, v1, s[8:9] offset:1024

.Lxb_l5:
	s_or_b64 exec, exec, s[0:1]
.LBB0_836:
	s_or_b64 exec, exec, s[0:1]
	s_mov_b64 s[0:1], exec
	v_mbcnt_lo_u32_b32 v0, s0, 0
	v_mbcnt_hi_u32_b32 v0, s1, v0
	v_cmp_eq_u32_e32 vcc, 0, v0
	s_waitcnt vmcnt(0)
	buffer_inv sc1
	s_and_saveexec_b64 s[4:5], vcc
	s_cbranch_execz .LBB0_838
	s_bcnt1_i32_b64 s0, s[0:1]
	v_mov_b32_e32 v0, 0x2000
	v_mov_b32_e32 v1, s0
	global_atomic_add v0, v1, s[10:11] offset:1024

.Lxb_l6:
	s_or_b64 exec, exec, s[0:1]
.LBB0_904:
	s_or_b64 exec, exec, s[0:1]
	s_mov_b64 s[0:1], exec
	v_mbcnt_lo_u32_b32 v0, s0, 0
	v_mbcnt_hi_u32_b32 v0, s1, v0
	v_cmp_eq_u32_e32 vcc, 0, v0
	s_waitcnt vmcnt(0)
	buffer_inv sc1
	s_and_saveexec_b64 s[4:5], vcc
	s_cbranch_execz .LBB0_906
	s_bcnt1_i32_b64 s0, s[0:1]
	v_mov_b32_e32 v0, 0x2000
	v_mov_b32_e32 v1, s0
	global_atomic_add v0, v1, s[8:9] offset:1024

.Lxb_l7:
	s_or_b64 exec, exec, s[0:1]
.LBB0_976:
	s_or_b64 exec, exec, s[0:1]
	s_mov_b64 s[0:1], exec
	v_mbcnt_lo_u32_b32 v0, s0, 0
	v_mbcnt_hi_u32_b32 v0, s1, v0
	v_cmp_eq_u32_e32 vcc, 0, v0
	s_waitcnt vmcnt(0)
	buffer_inv sc1
	s_and_saveexec_b64 s[4:5], vcc
	s_cbranch_execz .LBB0_978
	s_bcnt1_i32_b64 s0, s[0:1]
	v_mov_b32_e32 v0, 0x2000
	v_mov_b32_e32 v1, s0
	global_atomic_add v0, v1, s[8:9] offset:1024

.Lxb_l8:
	s_or_b64 exec, exec, s[0:1]
.LBB0_1079:
	s_or_b64 exec, exec, s[0:1]
	s_mov_b64 s[0:1], exec
	v_mbcnt_lo_u32_b32 v0, s0, 0
	v_mbcnt_hi_u32_b32 v0, s1, v0
	v_cmp_eq_u32_e32 vcc, 0, v0
	s_waitcnt vmcnt(0)
	buffer_inv sc1
	s_and_saveexec_b64 s[4:5], vcc
	s_cbranch_execz .LBB0_1081
	s_bcnt1_i32_b64 s0, s[0:1]
	v_mov_b32_e32 v0, 0x2000
	v_mov_b32_e32 v1, s0
	global_atomic_add v0, v1, s[8:9] offset:1024

.Lxb_l9:
	s_or_b64 exec, exec, s[0:1]
.LBB0_1152:
	s_or_b64 exec, exec, s[0:1]
	s_mov_b64 s[0:1], exec
	v_mbcnt_lo_u32_b32 v0, s0, 0
	v_mbcnt_hi_u32_b32 v0, s1, v0
	v_cmp_eq_u32_e32 vcc, 0, v0
	s_waitcnt vmcnt(0)
	buffer_inv sc1
	s_and_saveexec_b64 s[4:5], vcc
	s_cbranch_execz .LBB0_1154
	s_bcnt1_i32_b64 s0, s[0:1]
	v_mov_b32_e32 v0, 0x2000
	v_mov_b32_e32 v1, s0
	global_atomic_add v0, v1, s[8:9] offset:1024

.Lxb_l10:
	s_or_b64 exec, exec, s[0:1]
.LBB0_1224:
	s_or_b64 exec, exec, s[0:1]
	s_mov_b64 s[0:1], exec
	v_mbcnt_lo_u32_b32 v0, s0, 0
	v_mbcnt_hi_u32_b32 v0, s1, v0
	v_cmp_eq_u32_e32 vcc, 0, v0
	s_waitcnt vmcnt(0)
	buffer_inv sc1
	s_and_saveexec_b64 s[4:5], vcc
	s_cbranch_execz .LBB0_1226
	s_bcnt1_i32_b64 s0, s[0:1]
	v_mov_b32_e32 v0, 0x2000
	v_mov_b32_e32 v1, s0
	global_atomic_add v0, v1, s[8:9] offset:1024

.Lxb_l11:
	s_or_b64 exec, exec, s[0:1]
.LBB0_1288:
	s_or_b64 exec, exec, s[0:1]
	s_mov_b64 s[0:1], exec
	v_mbcnt_lo_u32_b32 v0, s0, 0
	v_mbcnt_hi_u32_b32 v0, s1, v0
	v_cmp_eq_u32_e32 vcc, 0, v0
	s_waitcnt vmcnt(0)
	buffer_inv sc1
	s_and_saveexec_b64 s[4:5], vcc
	s_cbranch_execz .LBB0_1290
	s_bcnt1_i32_b64 s0, s[0:1]
	v_mov_b32_e32 v0, 0x2000
	v_mov_b32_e32 v1, s0
	global_atomic_add v0, v1, s[8:9] offset:1024

.Lxb_l12:
	s_or_b64 exec, exec, s[0:1]
.LBB0_1368:
	s_or_b64 exec, exec, s[0:1]
	s_mov_b64 s[0:1], exec
	v_mbcnt_lo_u32_b32 v0, s0, 0
	v_mbcnt_hi_u32_b32 v0, s1, v0
	v_cmp_eq_u32_e32 vcc, 0, v0
	s_waitcnt vmcnt(0)
	buffer_inv sc1
	s_and_saveexec_b64 s[4:5], vcc
	s_cbranch_execz .LBB0_1370
	s_bcnt1_i32_b64 s0, s[0:1]
	v_mov_b32_e32 v0, 0x2000
	v_mov_b32_e32 v1, s0
	global_atomic_add v0, v1, s[8:9] offset:1024

.Lxb_l13:
	s_or_b64 exec, exec, s[0:1]
.LBB0_1462:
	s_or_b64 exec, exec, s[0:1]
	s_mov_b64 s[0:1], exec
	v_mbcnt_lo_u32_b32 v0, s0, 0
	v_mbcnt_hi_u32_b32 v0, s1, v0
	v_cmp_eq_u32_e32 vcc, 0, v0
	s_waitcnt vmcnt(0)
	buffer_inv sc1
	s_and_saveexec_b64 s[4:5], vcc
	s_cbranch_execz .LBB0_1464
	s_bcnt1_i32_b64 s0, s[0:1]
	v_mov_b32_e32 v0, 0x2000
	v_mov_b32_e32 v1, s0
	global_atomic_add v0, v1, s[8:9] offset:1024

.Lxb_l14:
	s_or_b64 exec, exec, s[0:1]
.LBB0_1518:
	s_or_b64 exec, exec, s[0:1]
	s_mov_b64 s[0:1], exec
	v_mbcnt_lo_u32_b32 v0, s0, 0
	v_mbcnt_hi_u32_b32 v0, s1, v0
	v_cmp_eq_u32_e32 vcc, 0, v0
	s_waitcnt vmcnt(0)
	buffer_inv sc1
	s_and_saveexec_b64 s[4:5], vcc
	s_cbranch_execz .LBB0_1520
	s_bcnt1_i32_b64 s0, s[0:1]
	v_mov_b32_e32 v0, 0x2000
	v_mov_b32_e32 v1, s0
	global_atomic_add v0, v1, s[8:9] offset:1024

.Lxb_l15:
	s_or_b64 exec, exec, s[0:1]
.LBB0_1594:
	s_or_b64 exec, exec, s[0:1]
	s_mov_b64 s[0:1], exec
	v_mbcnt_lo_u32_b32 v0, s0, 0
	v_mbcnt_hi_u32_b32 v0, s1, v0
	v_cmp_eq_u32_e32 vcc, 0, v0
	s_waitcnt vmcnt(0)
	buffer_inv sc1
	s_and_saveexec_b64 s[4:5], vcc
	s_cbranch_execz .LBB0_1596
	s_bcnt1_i32_b64 s0, s[0:1]
	v_mov_b32_e32 v0, 0x2000
	v_mov_b32_e32 v1, s0
	global_atomic_add v0, v1, s[8:9] offset:1024

.Lxb_l16:
	s_or_b64 exec, exec, s[0:1]
.LBB0_1666:
	s_or_b64 exec, exec, s[0:1]
	s_mov_b64 s[0:1], exec
	v_mbcnt_lo_u32_b32 v0, s0, 0
	v_mbcnt_hi_u32_b32 v0, s1, v0
	v_cmp_eq_u32_e32 vcc, 0, v0
	s_waitcnt vmcnt(0)
	buffer_inv sc1
	s_and_saveexec_b64 s[4:5], vcc
	s_cbranch_execz .LBB0_1668
	s_bcnt1_i32_b64 s0, s[0:1]
	v_mov_b32_e32 v0, 0x2000
	v_mov_b32_e32 v1, s0
	global_atomic_add v0, v1, s[8:9] offset:1024

.Lxb_l17:
	s_or_b64 exec, exec, s[0:1]
.LBB0_1730:
	s_or_b64 exec, exec, s[0:1]
	s_mov_b64 s[0:1], exec
	v_mbcnt_lo_u32_b32 v0, s0, 0
	v_mbcnt_hi_u32_b32 v0, s1, v0
	v_cmp_eq_u32_e32 vcc, 0, v0
	s_waitcnt vmcnt(0)
	buffer_inv sc1
	s_and_saveexec_b64 s[4:5], vcc
	s_cbranch_execz .LBB0_1732
	s_bcnt1_i32_b64 s0, s[0:1]
	v_mov_b32_e32 v0, 0x2000
	v_mov_b32_e32 v1, s0
	global_atomic_add v0, v1, s[8:9] offset:1024

.LBB0_1789:
	s_or_b64 exec, exec, s[8:9]
	v_cvt_f32_u32_e32 v3, v0
	s_waitcnt vmcnt(0)
	v_readfirstlane_b32 s0, v2
	s_add_u32 s8, s26, 0xc3500
	s_addc_u32 s9, s27, 0
	v_rcp_iflag_f32_e32 v3, v3
	v_add_u32_e32 v1, s0, v1
	v_add_u32_e32 v4, 1, v1
	s_mov_b64 s[10:11], -1
	v_mul_f32_e32 v2, 0x4f7ffffe, v3
	v_cvt_u32_f32_e32 v2, v2
	v_sub_u32_e32 v3, 0, v0
	v_mul_lo_u32 v3, v3, v2
	v_mul_hi_u32 v3, v2, v3
	v_add_u32_e32 v2, v2, v3
	v_mul_hi_u32 v2, v1, v2
	v_mul_lo_u32 v3, v2, v0
	v_sub_u32_e32 v1, v1, v3
	v_add_u32_e32 v5, 1, v2
	v_cmp_ge_u32_e32 vcc, v1, v0
	v_sub_u32_e32 v3, v1, v0
	s_nop 0
	v_cndmask_b32_e32 v2, v2, v5, vcc
	v_cndmask_b32_e32 v1, v1, v3, vcc
	v_add_u32_e32 v3, 1, v2
	v_cmp_ge_u32_e32 vcc, v1, v0
	s_nop 1
	v_cndmask_b32_e32 v2, v2, v3, vcc
	v_mul_lo_u32 v1, v0, v2
	v_add_u32_e32 v0, v1, v0
	v_cmp_ne_u32_e32 vcc, v4, v0
	s_and_saveexec_b64 s[0:1], vcc
	s_cbranch_execz .Lxb_l18
	v_mov_b32_e32 v1, 0xc3000
	s_mov_b32 s12, 0

.Lxb_l18:
	s_or_b64 exec, exec, s[0:1]
.LBB0_1803:
	s_or_b64 exec, exec, s[0:1]
	s_mov_b64 s[0:1], exec
	v_mbcnt_lo_u32_b32 v0, s0, 0
	v_mbcnt_hi_u32_b32 v0, s1, v0
	v_cmp_eq_u32_e32 vcc, 0, v0
	s_waitcnt vmcnt(0)
	buffer_inv sc1
	s_and_saveexec_b64 s[8:9], vcc
	s_cbranch_execz .LBB0_1805
	s_bcnt1_i32_b64 s0, s[0:1]
	v_mov_b32_e32 v0, 0x2000
	v_mov_b32_e32 v1, s0
	global_atomic_add v0, v1, s[4:5] offset:1024
